# P0 rmsnorm: gain vector loaded once per wave instead of per row with dependent waits; row stores issued back to back
# speedup vs baseline: 1.0119x; 1.0119x over previous
; __device__ __forceinline__ unsigned cvtpk(float lo, float hi) { f32x2 v = {lo, hi}; bf16x2_t b = __builtin_convertvector(v, bf16x2_t); return __builtin_bit_cast(unsigned, b); }
; __device__ __forceinline__ float wave_sum(float v) {
; #pragma unroll
;     for (int o = 1; o < 64; o <<= 1) v += __shfl_xor(v, o);
;     return v;
; }
; __global__ void __launch_bounds__(NWAVES * 64, 2) fwd(Args args) {
;     ...
;         for (int m = gw; m < M; m += NGW) {
;             const f32x4* xr = (const f32x4*)(x + (size_t)m * DM) + lane;
;             f32x4 v[8]; float s = 0.f;
; #pragma unroll
;             for (int j = 0; j < 8; ++j) { v[j] = __builtin_nontemporal_load(xr + 64 * j); s += (v[j].x * v[j].x + v[j].y * v[j].y) + (v[j].z * v[j].z + v[j].w * v[j].w); }
;             const float rs = rsqrtf(wave_sum(s) * (1.0f / DM) + EPS);
;             u32x2* o8 = (u32x2*)(U + (size_t)m * DM) + lane;
; #pragma unroll
;             for (int j = 0; j < 8; ++j) { const f32x4 g = ((const f32x4*)attn_norm)[lane + 64 * j]; u32x2 w; w.x = cvtpk(v[j].x * rs * g.x, v[j].y * rs * g.y); w.y = cvtpk(v[j].z * rs * g.z, v[j].w * rs * g.w); o8[64 * j] = w; }
.LBB0_16:
	s_cmpk_gt_i32 s4, 0x1fff
	s_cbranch_scc1 .LBB0_19
	v_and_b32_e32 v0, 64, v8
	v_add_u32_e32 v0, 64, v0
	v_xor_b32_e32 v1, 1, v8
	v_cmp_lt_i32_e32 vcc, v1, v0
	v_ashrrev_i32_e32 v17, 31, v16
	s_waitcnt lgkmcnt(0)
	s_mov_b64 s[14:15], 0x1000
	v_cndmask_b32_e32 v1, v8, v1, vcc
	v_lshlrev_b32_e32 v32, 2, v1
	v_xor_b32_e32 v1, 2, v8
	v_cmp_lt_i32_e32 vcc, v1, v0
	s_ashr_i32 s5, s4, 31
	s_nop 0
	v_cndmask_b32_e32 v1, v8, v1, vcc
	v_lshlrev_b32_e32 v33, 2, v1
	v_xor_b32_e32 v1, 4, v8
	v_cmp_lt_i32_e32 vcc, v1, v0
	s_nop 1
	v_cndmask_b32_e32 v1, v8, v1, vcc
	v_lshlrev_b32_e32 v34, 2, v1
	v_xor_b32_e32 v1, 8, v8
	v_cmp_lt_i32_e32 vcc, v1, v0
	s_nop 1
	v_cndmask_b32_e32 v1, v8, v1, vcc
	v_lshlrev_b32_e32 v35, 2, v1
	v_xor_b32_e32 v1, 16, v8
	v_cmp_lt_i32_e32 vcc, v1, v0
	s_nop 1
	v_cndmask_b32_e32 v1, v8, v1, vcc
	v_lshlrev_b32_e32 v36, 2, v1
	v_xor_b32_e32 v1, 32, v8
	v_cmp_lt_i32_e32 vcc, v1, v0
	s_nop 1
	v_cndmask_b32_e32 v0, v8, v1, vcc
	v_lshlrev_b32_e32 v37, 2, v0
	v_lshlrev_b64 v[0:1], 4, v[16:17]
	v_lshl_add_u64 v[18:19], s[20:21], 0, v[0:1]
	v_lshl_add_u64 v[20:21], v[18:19], 0, s[14:15]
	s_mov_b64 s[14:15], 0x1400
	v_lshl_add_u64 v[22:23], v[18:19], 0, s[14:15]
	s_mov_b64 s[14:15], 0x1800
	v_lshl_add_u64 v[24:25], v[18:19], 0, s[14:15]
	s_lshl_b64 s[14:15], s[4:5], 12
	s_add_u32 s14, s80, s14
	s_addc_u32 s15, s81, s15
	v_lshl_add_u64 v[2:3], v[16:17], 3, s[14:15]
	s_mov_b64 s[14:15], 0x2f00e00
	s_ashr_i32 s7, s6, 31
	v_lshl_add_u64 v[28:29], v[2:3], 0, s[14:15]
	s_lshl_b64 s[14:15], s[6:7], 12
	s_lshl_b64 s[22:23], s[4:5], 13
	s_add_u32 s16, s16, s22
	s_addc_u32 s17, s17, s23
	s_mov_b64 s[20:21], 0x1c00
	v_lshl_add_u64 v[0:1], s[16:17], 0, v[0:1]
	v_lshl_add_u64 v[26:27], v[18:19], 0, s[20:21]
	v_lshl_add_u64 v[30:31], v[0:1], 0, s[20:21]
	s_lshl_b64 s[16:17], s[6:7], 13
	v_mov_b32_e32 v17, 0x358637bd
	s_mov_b32 s5, 0x800000
	global_load_dwordx4 v[88:91], v[18:19], off
	global_load_dwordx4 v[92:95], v[18:19], off offset:1024
	global_load_dwordx4 v[96:99], v[18:19], off offset:2048
	global_load_dwordx4 v[100:103], v[18:19], off offset:3072
	global_load_dwordx4 v[104:107], v[20:21], off
	global_load_dwordx4 v[108:111], v[22:23], off
	global_load_dwordx4 v[112:115], v[24:25], off
	global_load_dwordx4 v[116:119], v[26:27], off
	s_waitcnt vmcnt(0)
; __device__ __forceinline__ unsigned cvtpk(float lo, float hi) { f32x2 v = {lo, hi}; bf16x2_t b = __builtin_convertvector(v, bf16x2_t); return __builtin_bit_cast(unsigned, b); }
; __global__ void __launch_bounds__(NWAVES * 64, 2) fwd(Args args) {
;     ...
;         for (int m = gw; m < M; m += NGW) {
;             const f32x4* xr = (const f32x4*)(x + (size_t)m * DM) + lane;
;             f32x4 v[8]; float s = 0.f;
; #pragma unroll
;             for (int j = 0; j < 8; ++j) { v[j] = __builtin_nontemporal_load(xr + 64 * j); s += (v[j].x * v[j].x + v[j].y * v[j].y) + (v[j].z * v[j].z + v[j].w * v[j].w); }
;             const float rs = rsqrtf(wave_sum(s) * (1.0f / DM) + EPS);
;             u32x2* o8 = (u32x2*)(U + (size_t)m * DM) + lane;
; #pragma unroll
;             for (int j = 0; j < 8; ++j) { const f32x4 g = ((const f32x4*)attn_norm)[lane + 64 * j]; u32x2 w; w.x = cvtpk(v[j].x * rs * g.x, v[j].y * rs * g.y); w.y = cvtpk(v[j].z * rs * g.z, v[j].w * rs * g.w); o8[64 * j] = w; }
;         }
.LBB0_18:
	v_add_co_u32_e32 v58, vcc, 0xfffff000, v30
	global_load_dwordx4 v[4:7], v[30:31], off offset:-3072 nt
	global_load_dwordx4 v[8:11], v[30:31], off offset:-2048 nt
	global_load_dwordx4 v[0:3], v[30:31], off nt
	v_addc_co_u32_e32 v59, vcc, -1, v31, vcc
	global_load_dwordx4 v[38:41], v[58:59], off offset:-3072 nt
	global_load_dwordx4 v[42:45], v[58:59], off offset:-2048 nt
	global_load_dwordx4 v[46:49], v[58:59], off offset:-1024 nt
	global_load_dwordx4 v[50:53], v[30:31], off offset:-4096 nt
	global_load_dwordx4 v[12:15], v[30:31], off offset:-1024 nt
	s_add_i32 s4, s4, s6
	s_cmpk_gt_i32 s4, 0x1fff
	v_lshl_add_u64 v[30:31], v[30:31], 0, s[16:17]
	s_waitcnt vmcnt(4)
	v_mov_b32_e32 v74, v41
	v_pk_mul_f32 v[58:59], v[10:11], v[10:11]
	v_pk_mul_f32 v[60:61], v[8:9], v[8:9]
	v_mul_f32_e32 v70, v2, v2
	s_waitcnt vmcnt(0)
	v_mul_f32_e32 v62, v13, v13
	v_mul_f32_e32 v64, v15, v15
	v_mul_f32_e32 v71, v3, v3
	v_pk_mov_b32 v[66:67], v[60:61], v[58:59] op_sel:[1,0]
	v_mov_b32_e32 v61, v59
	v_pk_fma_f32 v[58:59], v[12:13], v[12:13], v[62:63] op_sel_hi:[1,1,0]
	v_pk_fma_f32 v[62:63], v[14:15], v[14:15], v[64:65] op_sel_hi:[1,1,0]
	v_pk_mul_f32 v[68:69], v[48:49], v[48:49]
	v_pk_add_f32 v[60:61], v[66:67], v[60:61]
	v_pk_mul_f32 v[66:67], v[46:47], v[46:47]
	v_mov_b32_e32 v59, v70
	v_mov_b32_e32 v63, v71
	v_mov_b32_e32 v70, v39
	v_mov_b32_e32 v71, v43
	v_mov_b32_e32 v75, v45
	v_mov_b32_e32 v64, v38
	v_mov_b32_e32 v65, v42
	v_mov_b32_e32 v72, v40
	v_mov_b32_e32 v73, v44
	v_pk_mov_b32 v[80:81], v[66:67], v[68:69] op_sel:[1,0]
	v_mov_b32_e32 v67, v69
	v_pk_add_f32 v[58:59], v[58:59], v[62:63]
	v_pk_mul_f32 v[62:63], v[70:71], v[70:71]
	v_pk_mul_f32 v[68:69], v[74:75], v[74:75]
	v_pk_fma_f32 v[62:63], v[64:65], v[64:65], v[62:63]
	v_pk_fma_f32 v[64:65], v[72:73], v[72:73], v[68:69]
	v_mul_f32_e32 v77, v6, v6
	v_mul_f32_e32 v79, v7, v7
	v_mul_f32_e32 v76, v51, v51
	v_mul_f32_e32 v78, v53, v53
	v_pk_add_f32 v[66:67], v[80:81], v[66:67]
	v_pk_add_f32 v[62:63], v[62:63], v[64:65]
	v_mul_f32_e32 v83, v5, v5
	v_mul_f32_e32 v84, v4, v4
	v_pk_fma_f32 v[70:71], v[50:51], v[50:51], v[76:77] op_sel_hi:[1,1,0]
	v_pk_fma_f32 v[74:75], v[52:53], v[52:53], v[78:79] op_sel_hi:[1,1,0]
	v_pk_add_f32 v[66:67], v[66:67], v[66:67] op_sel:[0,1] op_sel_hi:[1,0]
	v_pk_add_f32 v[62:63], v[62:63], v[62:63] op_sel:[0,1] op_sel_hi:[1,0]
	v_mov_b32_e32 v71, v77
	v_mov_b32_e32 v75, v79
	v_mov_b32_e32 v67, v83
	v_mov_b32_e32 v63, v84
	v_pk_add_f32 v[64:65], v[70:71], v[74:75]
	v_pk_add_f32 v[62:63], v[62:63], v[66:67]
	v_mul_f32_e32 v82, v1, v1
	v_pk_add_f32 v[62:63], v[62:63], v[64:65]
	v_mul_f32_e32 v85, v0, v0
	v_pk_add_f32 v[60:61], v[60:61], v[60:61] op_sel:[0,1] op_sel_hi:[1,0]
	v_pk_add_f32 v[62:63], v[62:63], v[62:63] op_sel:[0,1] op_sel_hi:[1,0]
	v_mov_b32_e32 v61, v82
	v_mov_b32_e32 v63, v85
	v_pk_add_f32 v[60:61], v[62:63], v[60:61]
	s_nop 0
	v_pk_add_f32 v[58:59], v[60:61], v[58:59]
	s_nop 0
	v_add_f32_e32 v58, v58, v59
	ds_bpermute_b32 v59, v32, v58
	s_waitcnt lgkmcnt(0)
	v_add_f32_e32 v58, v58, v59
	ds_bpermute_b32 v59, v33, v58
	s_waitcnt lgkmcnt(0)
	v_add_f32_e32 v58, v58, v59
	ds_bpermute_b32 v59, v34, v58
	s_waitcnt lgkmcnt(0)
	v_add_f32_e32 v58, v58, v59
	ds_bpermute_b32 v59, v35, v58
	s_waitcnt lgkmcnt(0)
	v_add_f32_e32 v58, v58, v59
	ds_bpermute_b32 v59, v36, v58
	s_waitcnt lgkmcnt(0)
	v_add_f32_e32 v58, v58, v59
	ds_bpermute_b32 v59, v37, v58
	s_waitcnt lgkmcnt(0)
	v_add_f32_e32 v58, v58, v59
	v_fmamk_f32 v58, v58, 0x3a000000, v17
	v_mul_f32_e32 v59, 0x4b800000, v58
	v_cmp_gt_f32_e32 vcc, s5, v58
	s_nop 1
	v_cndmask_b32_e32 v58, v58, v59, vcc
	v_rsq_f32_e32 v58, v58
	s_nop 0
	v_mul_f32_e32 v59, 0x45800000, v58
	v_cndmask_b32_e32 v58, v58, v59, vcc
	v_pk_mul_f32 v[38:39], v[58:59], v[38:39] op_sel_hi:[0,1]
	v_pk_mul_f32 v[40:41], v[58:59], v[40:41] op_sel_hi:[0,1]
	v_pk_mul_f32 v[38:39], v[38:39], v[88:89]
	v_pk_mul_f32 v[40:41], v[40:41], v[90:91]
	v_cvt_pk_bf16_f32 v38, v38, v39
	v_cvt_pk_bf16_f32 v39, v40, v41
	global_store_dwordx2 v[28:29], v[38:39], off offset:-3584
	v_pk_mul_f32 v[42:43], v[58:59], v[42:43] op_sel_hi:[0,1]
	v_pk_mul_f32 v[44:45], v[58:59], v[44:45] op_sel_hi:[0,1]
	v_pk_mul_f32 v[42:43], v[42:43], v[92:93]
	v_pk_mul_f32 v[44:45], v[44:45], v[94:95]
	v_cvt_pk_bf16_f32 v42, v42, v43
	v_cvt_pk_bf16_f32 v43, v44, v45
	global_store_dwordx2 v[28:29], v[42:43], off offset:-3072
	v_pk_mul_f32 v[46:47], v[58:59], v[46:47] op_sel_hi:[0,1]
	v_pk_mul_f32 v[48:49], v[58:59], v[48:49] op_sel_hi:[0,1]
	v_pk_mul_f32 v[46:47], v[46:47], v[96:97]
	v_pk_mul_f32 v[48:49], v[48:49], v[98:99]
	v_cvt_pk_bf16_f32 v46, v46, v47
	v_cvt_pk_bf16_f32 v47, v48, v49
	global_store_dwordx2 v[28:29], v[46:47], off offset:-2560
	v_pk_mul_f32 v[50:51], v[58:59], v[50:51] op_sel_hi:[0,1]
	v_pk_mul_f32 v[52:53], v[58:59], v[52:53] op_sel_hi:[0,1]
	v_pk_mul_f32 v[50:51], v[50:51], v[100:101]
	v_pk_mul_f32 v[52:53], v[52:53], v[102:103]
	v_cvt_pk_bf16_f32 v50, v50, v51
	v_cvt_pk_bf16_f32 v51, v52, v53
	global_store_dwordx2 v[28:29], v[50:51], off offset:-2048
	v_pk_mul_f32 v[4:5], v[58:59], v[4:5] op_sel_hi:[0,1]
	v_pk_mul_f32 v[6:7], v[58:59], v[6:7] op_sel_hi:[0,1]
	v_pk_mul_f32 v[4:5], v[4:5], v[104:105]
	v_pk_mul_f32 v[6:7], v[6:7], v[106:107]
	v_cvt_pk_bf16_f32 v4, v4, v5
	v_cvt_pk_bf16_f32 v5, v6, v7
	global_store_dwordx2 v[28:29], v[4:5], off offset:-1536
	v_pk_mul_f32 v[8:9], v[58:59], v[8:9] op_sel_hi:[0,1]
	v_pk_mul_f32 v[10:11], v[58:59], v[10:11] op_sel_hi:[0,1]
	v_pk_mul_f32 v[8:9], v[8:9], v[108:109]
	v_pk_mul_f32 v[10:11], v[10:11], v[110:111]
	v_cvt_pk_bf16_f32 v8, v8, v9
	v_cvt_pk_bf16_f32 v9, v10, v11
	global_store_dwordx2 v[28:29], v[8:9], off offset:-1024
	v_pk_mul_f32 v[12:13], v[58:59], v[12:13] op_sel_hi:[0,1]
	v_pk_mul_f32 v[14:15], v[58:59], v[14:15] op_sel_hi:[0,1]
	v_pk_mul_f32 v[12:13], v[12:13], v[112:113]
	v_pk_mul_f32 v[14:15], v[14:15], v[114:115]
	v_cvt_pk_bf16_f32 v12, v12, v13
	v_cvt_pk_bf16_f32 v13, v14, v15
	global_store_dwordx2 v[28:29], v[12:13], off offset:-512
	v_pk_mul_f32 v[0:1], v[58:59], v[0:1] op_sel_hi:[0,1]
	v_pk_mul_f32 v[2:3], v[58:59], v[2:3] op_sel_hi:[0,1]
	v_pk_mul_f32 v[0:1], v[0:1], v[116:117]
	v_pk_mul_f32 v[2:3], v[2:3], v[118:119]
	v_cvt_pk_bf16_f32 v0, v0, v1
	v_cvt_pk_bf16_f32 v1, v2, v3
	global_store_dwordx2 v[28:29], v[0:1], off
	v_lshl_add_u64 v[28:29], v[28:29], 0, s[14:15]
	s_cbranch_scc0 .LBB0_18
